# phase 6 epilogue: pairs of 8-byte stores widened to 16-byte stores through v_permlane16_swap (32 -> 16 store instructions per wave per tile)
# speedup vs baseline: 1.0185x; 1.0094x over previous
; #define PG8_STAGE(bufoff, gbase, voff) do { _Pragma("unroll") for (int _i = 0; _i < 2; ++_i) \
;         __builtin_amdgcn_global_load_lds((const unsigned*)((const char*)(gbase) + (voff)[_i]), (PG8_LAS unsigned*)(lds + (bufoff) + ldsw + _i * 8192), 16, 0, 0); } while (0)
; #define PG8_LDA(dst, b, h) do { _Pragma("unroll") for (int m = 0; m < 4; ++m) _Pragma("unroll") for (int k = 0; k < 2; ++k) dst[m][k] = *(const PG8_LAS bf16x8*)(lds + PG8_SA(b, h) + aoff + m * 2048 + k * 1024); } while (0)
; #define PG8_LDB(dst, b, h) do { _Pragma("unroll") for (int n = 0; n < 2; ++n) _Pragma("unroll") for (int k = 0; k < 2; ++k) dst[n][k] = *(const PG8_LAS bf16x8*)(lds + PG8_SB(b, h) + boff + n * 2048 + k * 1024); } while (0)
; #define PG8_MMA(ai, bj, At, Bt) do { __builtin_amdgcn_s_setprio(1); _Pragma("unroll") for (int m = 0; m < 4; ++m) _Pragma("unroll") for (int n = 0; n < 2; ++n) _Pragma("unroll") for (int k = 0; k < 2; ++k) \
;         acc[ai][bj][m][n] = __builtin_amdgcn_mfma_f32_16x16x32_bf16(Bt[n][k], At[m][k], acc[ai][bj][m][n], 0, 0, 0); __builtin_amdgcn_s_setprio(0); } while (0)
; #define PG8_WAIT_V(n) asm volatile("s_waitcnt vmcnt(" #n ")" ::: "memory")
; #define PG8_WAIT_L(n) asm volatile("s_waitcnt lgkmcnt(" #n ")" ::: "memory")
; template <class Epi, class Sched>
; __device__ __forceinline__ void gemm_phase(PG8_LAS unsigned char* lds, const Gemm g, const Sched& S, const Epi& E) {
;     ...
;         for (int t = 0; t < nt; t += 2) {
;             const bool last = (t == nt - 2);
;             const char* a1 = cA + (size_t)(t + 1) * kstep;
;             const char* a2 = last ? nA : cA + (size_t)(t + 2) * kstep; const char* b2 = last ? nB : cB + (size_t)(t + 2) * kstep;
;             const char* a3 = a2 + kstep; const char* b3 = b2 + kstep;
;             PG8_LDB(B0, 0, 0); PG8_SCHED; PG8_LDA(At, 0, 0); PG8_STAGE(PG8_SA(1, 1), a1 + hstep, voffA);
;             PG8_WAIT_L(8); PG8_BAR; PG8_WAIT_L(0); PG8_MMA(0, 0, At, B0); PG8_BAR; PG8_SCHED;
;             PG8_LDB(B1, 0, 1); PG8_STAGE(PG8_SB(0, 0), b2, voffB);
;             PG8_BAR; PG8_WAIT_L(0); PG8_MMA(0, 1, At, B1); PG8_BAR;
;             PG8_LDA(At, 0, 1); PG8_STAGE(PG8_SA(0, 0), a2, voffA);
;             PG8_BAR; PG8_WAIT_L(0); PG8_MMA(1, 0, At, B0); PG8_BAR; PG8_SCHED;
;             PG8_STAGE(PG8_SB(0, 1), b2 + hstep, voffB);
;             PG8_WAIT_V(6); PG8_BAR; PG8_MMA(1, 1, At, B1); PG8_BAR;
.LBB0_800:
	ds_read_b128 v[138:141], v145
	ds_read_b128 v[162:165], v146
	ds_read_b128 v[166:169], v147
	ds_read_b128 v[170:173], v148
	s_add_u32 s28, s26, 0xfffc0080
	s_addc_u32 s29, s27, -1
	s_cmp_eq_u32 s58, 12
	s_cselect_b32 s31, s17, s29
	s_cselect_b32 s30, s54, s28
	s_cselect_b32 s29, s15, s57
	s_cselect_b32 s28, s55, s56
	s_mov_b32 m0, s51
	v_lshl_add_u64 v[206:207], s[26:27], 0, v[134:135]
	ds_read_b128 v[174:177], v143
	ds_read_b128 v[178:181], v143 offset:1024
	ds_read_b128 v[182:185], v143 offset:2048
	ds_read_b128 v[186:189], v143 offset:3072
	ds_read_b128 v[190:193], v143 offset:4096
	ds_read_b128 v[194:197], v143 offset:5120
	ds_read_b128 v[198:201], v143 offset:6144
	ds_read_b128 v[202:205], v143 offset:7168
	global_load_lds_dwordx4 v[206:207], off
	v_lshl_add_u64 v[206:207], s[26:27], 0, v[136:137]
	s_mov_b32 m0, s52
	s_nop 0
	global_load_lds_dwordx4 v[206:207], off
	s_waitcnt lgkmcnt(8)
	s_barrier
	s_waitcnt lgkmcnt(0)
	s_setprio 1
	s_waitcnt lgkmcnt(0)
	v_mfma_f32_16x16x32_bf16 v[126:129], v[138:141], v[174:177], v[126:129]
	v_mfma_f32_16x16x32_bf16 v[122:125], v[166:169], v[174:177], v[122:125]
	v_mfma_f32_16x16x32_bf16 v[110:113], v[138:141], v[182:185], v[110:113]
	v_mfma_f32_16x16x32_bf16 v[106:109], v[166:169], v[182:185], v[106:109]
	v_mfma_f32_16x16x32_bf16 v[94:97], v[138:141], v[190:193], v[94:97]
	v_mfma_f32_16x16x32_bf16 v[90:93], v[166:169], v[190:193], v[90:93]
	v_mfma_f32_16x16x32_bf16 v[78:81], v[138:141], v[198:201], v[78:81]
	v_mfma_f32_16x16x32_bf16 v[74:77], v[166:169], v[198:201], v[74:77]
	v_mfma_f32_16x16x32_bf16 v[126:129], v[162:165], v[178:181], v[126:129]
	v_mfma_f32_16x16x32_bf16 v[122:125], v[170:173], v[178:181], v[122:125]
	v_mfma_f32_16x16x32_bf16 v[110:113], v[162:165], v[186:189], v[110:113]
	v_mfma_f32_16x16x32_bf16 v[106:109], v[170:173], v[186:189], v[106:109]
	v_mfma_f32_16x16x32_bf16 v[94:97], v[162:165], v[194:197], v[94:97]
	v_mfma_f32_16x16x32_bf16 v[90:93], v[170:173], v[194:197], v[90:93]
	v_mfma_f32_16x16x32_bf16 v[78:81], v[162:165], v[202:205], v[78:81]
	v_mfma_f32_16x16x32_bf16 v[74:77], v[170:173], v[202:205], v[74:77]
	s_setprio 0
	s_barrier
	s_mov_b32 m0, s23
	v_lshl_add_u64 v[222:223], s[28:29], 0, v[130:131]
	ds_read_b128 v[206:209], v149
	ds_read_b128 v[210:213], v150
	ds_read_b128 v[214:217], v151
	ds_read_b128 v[218:221], v152
	global_load_lds_dwordx4 v[222:223], off
	v_lshl_add_u64 v[224:225], s[28:29], 0, v[132:133]
	s_mov_b32 m0, s25
	s_nop 0
	global_load_lds_dwordx4 v[224:225], off
	s_barrier
	s_waitcnt lgkmcnt(0)
	s_setprio 1
	s_waitcnt lgkmcnt(0)
	v_mfma_f32_16x16x32_bf16 v[118:121], v[206:209], v[174:177], v[118:121]
	v_mfma_f32_16x16x32_bf16 v[114:117], v[214:217], v[174:177], v[114:117]
	v_mfma_f32_16x16x32_bf16 v[102:105], v[206:209], v[182:185], v[102:105]
	v_mfma_f32_16x16x32_bf16 v[98:101], v[214:217], v[182:185], v[98:101]
	v_mfma_f32_16x16x32_bf16 v[86:89], v[206:209], v[190:193], v[86:89]
	v_mfma_f32_16x16x32_bf16 v[82:85], v[214:217], v[190:193], v[82:85]
	v_mfma_f32_16x16x32_bf16 v[70:73], v[206:209], v[198:201], v[70:73]
	v_mfma_f32_16x16x32_bf16 v[66:69], v[214:217], v[198:201], v[66:69]
	v_mfma_f32_16x16x32_bf16 v[118:121], v[210:213], v[178:181], v[118:121]
	v_mfma_f32_16x16x32_bf16 v[114:117], v[218:221], v[178:181], v[114:117]
	v_mfma_f32_16x16x32_bf16 v[102:105], v[210:213], v[186:189], v[102:105]
	v_mfma_f32_16x16x32_bf16 v[98:101], v[218:221], v[186:189], v[98:101]
	v_mfma_f32_16x16x32_bf16 v[86:89], v[210:213], v[194:197], v[86:89]
	v_mfma_f32_16x16x32_bf16 v[82:85], v[218:221], v[194:197], v[82:85]
	v_mfma_f32_16x16x32_bf16 v[70:73], v[210:213], v[202:205], v[70:73]
	v_mfma_f32_16x16x32_bf16 v[66:69], v[218:221], v[202:205], v[66:69]
	s_setprio 0
	s_mov_b32 m0, s38
	v_lshl_add_u64 v[226:227], s[30:31], 0, v[130:131]
	s_barrier
	ds_read_b128 v[174:177], v143 offset:16384
	ds_read_b128 v[178:181], v143 offset:17408
	ds_read_b128 v[182:185], v143 offset:18432
	ds_read_b128 v[186:189], v143 offset:19456
	ds_read_b128 v[190:193], v143 offset:20480
	ds_read_b128 v[194:197], v143 offset:21504
	ds_read_b128 v[198:201], v143 offset:22528
	ds_read_b128 v[202:205], v143 offset:23552
	global_load_lds_dwordx4 v[226:227], off
	v_lshl_add_u64 v[228:229], s[30:31], 0, v[132:133]
	s_mov_b32 m0, s39
	s_nop 0
	global_load_lds_dwordx4 v[228:229], off
	s_barrier
	s_waitcnt lgkmcnt(0)
	s_setprio 1
	s_waitcnt lgkmcnt(0)
	v_mfma_f32_16x16x32_bf16 v[62:65], v[138:141], v[174:177], v[62:65]
	v_mfma_f32_16x16x32_bf16 v[58:61], v[166:169], v[174:177], v[58:61]
	v_mfma_f32_16x16x32_bf16 v[46:49], v[138:141], v[182:185], v[46:49]
	v_mfma_f32_16x16x32_bf16 v[42:45], v[166:169], v[182:185], v[42:45]
	v_mfma_f32_16x16x32_bf16 v[30:33], v[138:141], v[190:193], v[30:33]
	v_mfma_f32_16x16x32_bf16 v[26:29], v[166:169], v[190:193], v[26:29]
	v_mfma_f32_16x16x32_bf16 v[14:17], v[138:141], v[198:201], v[14:17]
	v_mfma_f32_16x16x32_bf16 v[10:13], v[166:169], v[198:201], v[10:13]
	v_mfma_f32_16x16x32_bf16 v[62:65], v[162:165], v[178:181], v[62:65]
	v_mfma_f32_16x16x32_bf16 v[58:61], v[170:173], v[178:181], v[58:61]
	v_mfma_f32_16x16x32_bf16 v[46:49], v[162:165], v[186:189], v[46:49]
	v_mfma_f32_16x16x32_bf16 v[42:45], v[170:173], v[186:189], v[42:45]
	v_mfma_f32_16x16x32_bf16 v[30:33], v[162:165], v[194:197], v[30:33]
	v_mfma_f32_16x16x32_bf16 v[26:29], v[170:173], v[194:197], v[26:29]
	v_mfma_f32_16x16x32_bf16 v[14:17], v[162:165], v[202:205], v[14:17]
	v_mfma_f32_16x16x32_bf16 v[10:13], v[170:173], v[202:205], v[10:13]
	s_setprio 0
	s_barrier
; #define PG8_STAGE(bufoff, gbase, voff) do { _Pragma("unroll") for (int _i = 0; _i < 2; ++_i) \
;         __builtin_amdgcn_global_load_lds((const unsigned*)((const char*)(gbase) + (voff)[_i]), (PG8_LAS unsigned*)(lds + (bufoff) + ldsw + _i * 8192), 16, 0, 0); } while (0)
; #define PG8_LDA(dst, b, h) do { _Pragma("unroll") for (int m = 0; m < 4; ++m) _Pragma("unroll") for (int k = 0; k < 2; ++k) dst[m][k] = *(const PG8_LAS bf16x8*)(lds + PG8_SA(b, h) + aoff + m * 2048 + k * 1024); } while (0)
; #define PG8_LDB(dst, b, h) do { _Pragma("unroll") for (int n = 0; n < 2; ++n) _Pragma("unroll") for (int k = 0; k < 2; ++k) dst[n][k] = *(const PG8_LAS bf16x8*)(lds + PG8_SB(b, h) + boff + n * 2048 + k * 1024); } while (0)
; #define PG8_MMA(ai, bj, At, Bt) do { __builtin_amdgcn_s_setprio(1); _Pragma("unroll") for (int m = 0; m < 4; ++m) _Pragma("unroll") for (int n = 0; n < 2; ++n) _Pragma("unroll") for (int k = 0; k < 2; ++k) \
;         acc[ai][bj][m][n] = __builtin_amdgcn_mfma_f32_16x16x32_bf16(Bt[n][k], At[m][k], acc[ai][bj][m][n], 0, 0, 0); __builtin_amdgcn_s_setprio(0); } while (0)
; #define PG8_WAIT_V(n) asm volatile("s_waitcnt vmcnt(" #n ")" ::: "memory")
; #define PG8_WAIT_L(n) asm volatile("s_waitcnt lgkmcnt(" #n ")" ::: "memory")
; #define PG8_BAR __builtin_amdgcn_s_barrier()
; #define PG8_SCHED __builtin_amdgcn_sched_barrier(0)
; template <class Epi, class Sched>
; __device__ __forceinline__ void gemm_phase(PG8_LAS unsigned char* lds, const Gemm g, const Sched& S, const Epi& E) {
;     ...
;             PG8_STAGE(PG8_SB(0, 1), b2 + hstep, voffB);
;             PG8_WAIT_V(6); PG8_BAR; PG8_MMA(1, 1, At, B1); PG8_BAR;
;             PG8_LDB(B0, 1, 0); PG8_SCHED; PG8_LDA(At, 1, 0); PG8_STAGE(PG8_SA(0, 1), a2 + hstep, voffA);
;             PG8_WAIT_L(8); PG8_BAR; PG8_WAIT_L(0); PG8_MMA(0, 0, At, B0); PG8_BAR; PG8_SCHED;
;             PG8_LDB(B1, 1, 1); PG8_STAGE(PG8_SB(1, 0), b3, voffB);
;             PG8_BAR; PG8_WAIT_L(0); PG8_MMA(0, 1, At, B1); PG8_BAR;
;             PG8_LDA(At, 1, 1); PG8_STAGE(PG8_SA(1, 0), a3, voffA);
;             PG8_BAR; PG8_WAIT_L(0); PG8_MMA(1, 0, At, B0); PG8_BAR; PG8_SCHED;
;             PG8_STAGE(PG8_SB(1, 1), b3 + hstep, voffB);
;             PG8_WAIT_V(6); PG8_BAR; PG8_MMA(1, 1, At, B1); PG8_BAR;
	s_add_u32 s60, s28, 0x40000
	s_addc_u32 s61, s29, 0
	s_mov_b32 m0, s40
	v_lshl_add_u64 v[138:139], s[60:61], 0, v[130:131]
	global_load_lds_dwordx4 v[138:139], off
	v_lshl_add_u64 v[138:139], s[60:61], 0, v[132:133]
	s_mov_b32 m0, s41
	s_nop 0
	global_load_lds_dwordx4 v[138:139], off
	s_waitcnt vmcnt(6)
	s_barrier
	s_setprio 1
	v_mfma_f32_16x16x32_bf16 v[54:57], v[206:209], v[174:177], v[54:57]
	v_mfma_f32_16x16x32_bf16 v[50:53], v[214:217], v[174:177], v[50:53]
	v_mfma_f32_16x16x32_bf16 v[38:41], v[206:209], v[182:185], v[38:41]
	v_mfma_f32_16x16x32_bf16 v[34:37], v[214:217], v[182:185], v[34:37]
	v_mfma_f32_16x16x32_bf16 v[22:25], v[206:209], v[190:193], v[22:25]
	v_mfma_f32_16x16x32_bf16 v[18:21], v[214:217], v[190:193], v[18:21]
	v_mfma_f32_16x16x32_bf16 v[6:9], v[206:209], v[198:201], v[6:9]
	v_mfma_f32_16x16x32_bf16 v[2:5], v[214:217], v[198:201], v[2:5]
	v_mfma_f32_16x16x32_bf16 v[54:57], v[210:213], v[178:181], v[54:57]
	v_mfma_f32_16x16x32_bf16 v[50:53], v[218:221], v[178:181], v[50:53]
	v_mfma_f32_16x16x32_bf16 v[38:41], v[210:213], v[186:189], v[38:41]
	v_mfma_f32_16x16x32_bf16 v[34:37], v[218:221], v[186:189], v[34:37]
	v_mfma_f32_16x16x32_bf16 v[22:25], v[210:213], v[194:197], v[22:25]
	v_mfma_f32_16x16x32_bf16 v[18:21], v[218:221], v[194:197], v[18:21]
	v_mfma_f32_16x16x32_bf16 v[6:9], v[210:213], v[202:205], v[6:9]
	v_mfma_f32_16x16x32_bf16 v[2:5], v[218:221], v[202:205], v[2:5]
	s_setprio 0
	s_barrier
	ds_read_b128 v[138:141], v153
	ds_read_b128 v[162:165], v154
	ds_read_b128 v[166:169], v155
	ds_read_b128 v[170:173], v156
	s_add_u32 s30, s30, 0x40000
	s_addc_u32 s31, s31, 0
	s_mov_b32 m0, s42
	v_lshl_add_u64 v[206:207], s[30:31], 0, v[130:131]
	ds_read_b128 v[174:177], v143 offset:32768
	ds_read_b128 v[178:181], v143 offset:33792
	ds_read_b128 v[182:185], v143 offset:34816
	ds_read_b128 v[186:189], v143 offset:35840
	ds_read_b128 v[190:193], v143 offset:36864
	ds_read_b128 v[194:197], v143 offset:37888
	ds_read_b128 v[198:201], v143 offset:38912
	ds_read_b128 v[202:205], v143 offset:39936
	global_load_lds_dwordx4 v[206:207], off
	v_lshl_add_u64 v[206:207], s[30:31], 0, v[132:133]
	s_mov_b32 m0, s43
	s_nop 0
	global_load_lds_dwordx4 v[206:207], off
	s_waitcnt lgkmcnt(8)
	s_barrier
	s_waitcnt lgkmcnt(0)
	s_setprio 1
	s_waitcnt lgkmcnt(0)
	v_mfma_f32_16x16x32_bf16 v[126:129], v[138:141], v[174:177], v[126:129]
	v_mfma_f32_16x16x32_bf16 v[122:125], v[166:169], v[174:177], v[122:125]
	v_mfma_f32_16x16x32_bf16 v[110:113], v[138:141], v[182:185], v[110:113]
	v_mfma_f32_16x16x32_bf16 v[106:109], v[166:169], v[182:185], v[106:109]
	v_mfma_f32_16x16x32_bf16 v[94:97], v[138:141], v[190:193], v[94:97]
	v_mfma_f32_16x16x32_bf16 v[90:93], v[166:169], v[190:193], v[90:93]
	v_mfma_f32_16x16x32_bf16 v[78:81], v[138:141], v[198:201], v[78:81]
	v_mfma_f32_16x16x32_bf16 v[74:77], v[166:169], v[198:201], v[74:77]
	v_mfma_f32_16x16x32_bf16 v[126:129], v[162:165], v[178:181], v[126:129]
	v_mfma_f32_16x16x32_bf16 v[122:125], v[170:173], v[178:181], v[122:125]
	v_mfma_f32_16x16x32_bf16 v[110:113], v[162:165], v[186:189], v[110:113]
	v_mfma_f32_16x16x32_bf16 v[106:109], v[170:173], v[186:189], v[106:109]
	v_mfma_f32_16x16x32_bf16 v[94:97], v[162:165], v[194:197], v[94:97]
	v_mfma_f32_16x16x32_bf16 v[90:93], v[170:173], v[194:197], v[90:93]
	v_mfma_f32_16x16x32_bf16 v[78:81], v[162:165], v[202:205], v[78:81]
	v_mfma_f32_16x16x32_bf16 v[74:77], v[170:173], v[202:205], v[74:77]
	s_setprio 0
	s_barrier
	s_mov_b32 m0, s44
	v_lshl_add_u64 v[222:223], v[222:223], 0, s[8:9]
	ds_read_b128 v[206:209], v157
	ds_read_b128 v[210:213], v158
	ds_read_b128 v[214:217], v159
	ds_read_b128 v[218:221], v160
	global_load_lds_dwordx4 v[222:223], off
	v_lshl_add_u64 v[222:223], v[224:225], 0, s[8:9]
	s_mov_b32 m0, s45
	s_nop 0
	global_load_lds_dwordx4 v[222:223], off
	s_barrier
	s_waitcnt lgkmcnt(0)
	s_setprio 1
	s_waitcnt lgkmcnt(0)
	v_mfma_f32_16x16x32_bf16 v[118:121], v[206:209], v[174:177], v[118:121]
	v_mfma_f32_16x16x32_bf16 v[114:117], v[214:217], v[174:177], v[114:117]
	v_mfma_f32_16x16x32_bf16 v[102:105], v[206:209], v[182:185], v[102:105]
	v_mfma_f32_16x16x32_bf16 v[98:101], v[214:217], v[182:185], v[98:101]
	v_mfma_f32_16x16x32_bf16 v[86:89], v[206:209], v[190:193], v[86:89]
	v_mfma_f32_16x16x32_bf16 v[82:85], v[214:217], v[190:193], v[82:85]
	v_mfma_f32_16x16x32_bf16 v[70:73], v[206:209], v[198:201], v[70:73]
	v_mfma_f32_16x16x32_bf16 v[66:69], v[214:217], v[198:201], v[66:69]
	v_mfma_f32_16x16x32_bf16 v[118:121], v[210:213], v[178:181], v[118:121]
	v_mfma_f32_16x16x32_bf16 v[114:117], v[218:221], v[178:181], v[114:117]
	v_mfma_f32_16x16x32_bf16 v[102:105], v[210:213], v[186:189], v[102:105]
	v_mfma_f32_16x16x32_bf16 v[98:101], v[218:221], v[186:189], v[98:101]
	v_mfma_f32_16x16x32_bf16 v[86:89], v[210:213], v[194:197], v[86:89]
	v_mfma_f32_16x16x32_bf16 v[82:85], v[218:221], v[194:197], v[82:85]
	v_mfma_f32_16x16x32_bf16 v[70:73], v[210:213], v[202:205], v[70:73]
	v_mfma_f32_16x16x32_bf16 v[66:69], v[218:221], v[202:205], v[66:69]
	s_setprio 0
	s_mov_b32 m0, s46
	v_lshl_add_u64 v[222:223], v[226:227], 0, s[8:9]
	s_barrier
	ds_read_b128 v[174:177], v143 offset:49152
	ds_read_b128 v[178:181], v143 offset:50176
	ds_read_b128 v[182:185], v143 offset:51200
	ds_read_b128 v[186:189], v143 offset:52224
	ds_read_b128 v[190:193], v143 offset:53248
	ds_read_b128 v[194:197], v143 offset:54272
	ds_read_b128 v[198:201], v143 offset:55296
	ds_read_b128 v[202:205], v143 offset:56320
	global_load_lds_dwordx4 v[222:223], off
	v_lshl_add_u64 v[222:223], v[228:229], 0, s[8:9]
	s_mov_b32 m0, s47
	s_nop 0
	global_load_lds_dwordx4 v[222:223], off
	s_barrier
; #define PG8_MMA(ai, bj, At, Bt) do { __builtin_amdgcn_s_setprio(1); _Pragma("unroll") for (int m = 0; m < 4; ++m) _Pragma("unroll") for (int n = 0; n < 2; ++n) _Pragma("unroll") for (int k = 0; k < 2; ++k) \
;         acc[ai][bj][m][n] = __builtin_amdgcn_mfma_f32_16x16x32_bf16(Bt[n][k], At[m][k], acc[ai][bj][m][n], 0, 0, 0); __builtin_amdgcn_s_setprio(0); } while (0)
; #define PG8_WAIT_V(n) asm volatile("s_waitcnt vmcnt(" #n ")" ::: "memory")
; #define PG8_BAR __builtin_amdgcn_s_barrier()
; template <class Epi, class Sched>
; __device__ __forceinline__ void gemm_phase(PG8_LAS unsigned char* lds, const Gemm g, const Sched& S, const Epi& E) {
;     ...
;             PG8_WAIT_V(6); PG8_BAR; PG8_MMA(1, 1, At, B1); PG8_BAR;
;         }
;         E(acc, cur, wr, wc, fr, fq);
;   __device__ __forceinline__ void operator()(const acc8_t& acc, const pg8::Unit& u, int wr, int wc, int fr, int fq) const {
;     u16* H = (u16*)(ws + OFF_H);
;     const float* rss = (const float*)(ws + OFF_ROWSS);
; #pragma unroll
;     for (int ai = 0; ai < 2; ai++)
; #pragma unroll
;       for (int m = 0; m < 4; m++) {
;         const size_t token = EPI_TOKEN(u, ai, m);
;         const float rs = rsqrtf(rss[token] * (1.f / 1024.f) + 1e-6f);
; #pragma unroll
;         for (int bj = 0; bj < 2; bj++)
; #pragma unroll
;           for (int n = 0; n < 2; n++) {
;             const int f = EPI_COL(u, bj, n);
;             const float v0 = fmaxf(acc[ai][bj][m][n][0] * rs, 0.f), v1 = fmaxf(acc[ai][bj][m][n][1] * rs, 0.f);
;             const float v2 = fmaxf(acc[ai][bj][m][n][2] * rs, 0.f), v3 = fmaxf(acc[ai][bj][m][n][3] * rs, 0.f);
;             uint2 o; o.x = pack2(v0 * v0, v1 * v1); o.y = pack2(v2 * v2, v3 * v3);
;             *(uint2*)(H + token * 4096 + f) = o;
;           }
;       }
;   }
	s_waitcnt lgkmcnt(0)
	s_setprio 1
	s_waitcnt lgkmcnt(0)
	v_mfma_f32_16x16x32_bf16 v[62:65], v[138:141], v[174:177], v[62:65]
	v_mfma_f32_16x16x32_bf16 v[58:61], v[166:169], v[174:177], v[58:61]
	v_mfma_f32_16x16x32_bf16 v[46:49], v[138:141], v[182:185], v[46:49]
	v_mfma_f32_16x16x32_bf16 v[42:45], v[166:169], v[182:185], v[42:45]
	v_mfma_f32_16x16x32_bf16 v[30:33], v[138:141], v[190:193], v[30:33]
	v_mfma_f32_16x16x32_bf16 v[26:29], v[166:169], v[190:193], v[26:29]
	v_mfma_f32_16x16x32_bf16 v[14:17], v[138:141], v[198:201], v[14:17]
	v_mfma_f32_16x16x32_bf16 v[10:13], v[166:169], v[198:201], v[10:13]
	v_mfma_f32_16x16x32_bf16 v[62:65], v[162:165], v[178:181], v[62:65]
	v_mfma_f32_16x16x32_bf16 v[58:61], v[170:173], v[178:181], v[58:61]
	v_mfma_f32_16x16x32_bf16 v[46:49], v[162:165], v[186:189], v[46:49]
	v_mfma_f32_16x16x32_bf16 v[42:45], v[170:173], v[186:189], v[42:45]
	v_mfma_f32_16x16x32_bf16 v[30:33], v[162:165], v[194:197], v[30:33]
	v_mfma_f32_16x16x32_bf16 v[26:29], v[170:173], v[194:197], v[26:29]
	v_mfma_f32_16x16x32_bf16 v[14:17], v[162:165], v[202:205], v[14:17]
	v_mfma_f32_16x16x32_bf16 v[10:13], v[170:173], v[202:205], v[10:13]
	s_setprio 0
	s_barrier
	s_add_u32 s28, s28, 0x40080
	s_addc_u32 s29, s29, 0
	s_mov_b32 m0, s48
	v_lshl_add_u64 v[138:139], s[28:29], 0, v[130:131]
	global_load_lds_dwordx4 v[138:139], off
	v_lshl_add_u64 v[138:139], s[28:29], 0, v[132:133]
	s_mov_b32 m0, s49
	s_nop 0
	global_load_lds_dwordx4 v[138:139], off
	s_waitcnt vmcnt(6)
	s_barrier
	s_setprio 1
	v_mfma_f32_16x16x32_bf16 v[54:57], v[206:209], v[174:177], v[54:57]
	v_mfma_f32_16x16x32_bf16 v[50:53], v[214:217], v[174:177], v[50:53]
	v_mfma_f32_16x16x32_bf16 v[38:41], v[206:209], v[182:185], v[38:41]
	v_mfma_f32_16x16x32_bf16 v[34:37], v[214:217], v[182:185], v[34:37]
	v_mfma_f32_16x16x32_bf16 v[22:25], v[206:209], v[190:193], v[22:25]
	v_mfma_f32_16x16x32_bf16 v[18:21], v[214:217], v[190:193], v[18:21]
	v_mfma_f32_16x16x32_bf16 v[6:9], v[206:209], v[198:201], v[6:9]
	v_mfma_f32_16x16x32_bf16 v[2:5], v[214:217], v[198:201], v[2:5]
	v_mfma_f32_16x16x32_bf16 v[54:57], v[210:213], v[178:181], v[54:57]
	v_mfma_f32_16x16x32_bf16 v[50:53], v[218:221], v[178:181], v[50:53]
	v_mfma_f32_16x16x32_bf16 v[38:41], v[210:213], v[186:189], v[38:41]
	v_mfma_f32_16x16x32_bf16 v[34:37], v[218:221], v[186:189], v[34:37]
	v_mfma_f32_16x16x32_bf16 v[22:25], v[210:213], v[194:197], v[22:25]
	v_mfma_f32_16x16x32_bf16 v[18:21], v[218:221], v[194:197], v[18:21]
	v_mfma_f32_16x16x32_bf16 v[6:9], v[210:213], v[202:205], v[6:9]
	v_mfma_f32_16x16x32_bf16 v[2:5], v[218:221], v[202:205], v[2:5]
	s_setprio 0
	s_add_i32 s58, s58, 2
	s_add_u32 s26, s26, 0x100
	s_addc_u32 s27, s27, 0
	s_add_u32 s56, s56, 0x100
	s_addc_u32 s57, s57, 0
	s_cmp_gt_u32 s58, 13
	s_barrier
	s_cbranch_scc0 .LBB0_800
	v_lshl_add_u32 v140, s24, 8, v142
	v_ashrrev_i32_e32 v141, 31, v140
	v_lshl_add_u64 v[138:139], v[140:141], 2, s[12:13]
	global_load_dword v166, v[138:139], off
	global_load_dword v176, v[138:139], off offset:64
	global_load_dword v177, v[138:139], off offset:128
	global_load_dword v178, v[138:139], off offset:192
	global_load_dword v179, v[138:139], off offset:512
	global_load_dword v180, v[138:139], off offset:576
	global_load_dword v181, v[138:139], off offset:640
	global_load_dword v182, v[138:139], off offset:704
	v_lshlrev_b64 v[164:165], 13, v[140:141]
	v_lshl_or_b32 v138, s22, 8, v144
	v_ashrrev_i32_e32 v139, 31, v138
	v_or_b32_e32 v162, 16, v140
	v_lshlrev_b64 v[138:139], 1, v[138:139]
	v_bfe_u32 v230, v0, 4, 1
	v_mul_u32_u24_e32 v230, 24, v230
	v_add_u32_e32 v138, v138, v230
	v_lshl_add_u64 v[164:165], s[10:11], 0, v[164:165]
	v_ashrrev_i32_e32 v163, 31, v162
	v_lshl_add_u64 v[164:165], v[164:165], 0, v[138:139]
	s_mov_b32 s22, s14
	s_mov_b32 s24, s16
	s_mov_b64 s[28:29], s[20:21]
	s_mov_b64 s[26:27], s[18:19]
	s_waitcnt vmcnt(0)
	v_fmamk_f32 v141, v166, 0x3a800000, v161
	v_mul_f32_e32 v166, 0x4b800000, v141
	v_cmp_gt_f32_e32 vcc, s53, v141
	s_nop 1
	v_cndmask_b32_e32 v141, v141, v166, vcc
	v_rsq_f32_e32 v141, v141
	v_lshl_add_u64 v[166:167], v[162:163], 2, s[12:13]
	v_mul_f32_e32 v168, 0x45800000, v141
	v_cndmask_b32_e32 v141, v141, v168, vcc
	v_mul_f32_e32 v126, v126, v141
	v_mul_f32_e32 v127, v127, v141
	v_mul_f32_e32 v128, v128, v141
	v_mul_f32_e32 v129, v129, v141
	v_mul_f32_e32 v122, v122, v141
	v_mul_f32_e32 v123, v123, v141
	v_mul_f32_e32 v124, v124, v141
	v_mul_f32_e32 v125, v125, v141
	v_mul_f32_e32 v168, v118, v141
	v_mul_f32_e32 v169, v119, v141
	v_mul_f32_e32 v170, v120, v141
	v_mul_f32_e32 v171, v121, v141
	v_mul_f32_e32 v172, v114, v141
	v_mul_f32_e32 v173, v115, v141
	v_mul_f32_e32 v174, v116, v141
	v_mul_f32_e32 v141, v117, v141
	v_max_f32_e32 v114, 0, v126
	v_max_f32_e32 v115, 0, v127
	v_max_f32_e32 v116, 0, v128
	v_max_f32_e32 v117, 0, v129
	v_max_f32_e32 v118, 0, v122
	v_max_f32_e32 v119, 0, v123
	v_max_f32_e32 v120, 0, v124
	v_max_f32_e32 v121, 0, v125
	v_max_f32_e32 v122, 0, v168
	v_max_f32_e32 v123, 0, v169
	v_max_f32_e32 v124, 0, v170
	v_max_f32_e32 v125, 0, v171
	v_max_f32_e32 v126, 0, v172
	v_max_f32_e32 v127, 0, v173
	v_max_f32_e32 v128, 0, v174
	v_max_f32_e32 v129, 0, v141
	v_pk_mul_f32 v[114:115], v[114:115], v[114:115]
	v_pk_mul_f32 v[116:117], v[116:117], v[116:117]
	v_pk_mul_f32 v[118:119], v[118:119], v[118:119]
	v_pk_mul_f32 v[120:121], v[120:121], v[120:121]
	v_pk_mul_f32 v[122:123], v[122:123], v[122:123]
	v_pk_mul_f32 v[124:125], v[124:125], v[124:125]
	v_pk_mul_f32 v[126:127], v[126:127], v[126:127]
	v_pk_mul_f32 v[128:129], v[128:129], v[128:129]
	v_cvt_pk_bf16_f32 v114, v114, v115
	v_cvt_pk_bf16_f32 v115, v116, v117
	v_cvt_pk_bf16_f32 v116, v118, v119
;   __device__ __forceinline__ void operator()(const acc8_t& acc, const pg8::Unit& u, int wr, int wc, int fr, int fq) const {
;     ...
; #pragma unroll
;     for (int ai = 0; ai < 2; ai++)
; #pragma unroll
;       for (int m = 0; m < 4; m++) {
;         const size_t token = EPI_TOKEN(u, ai, m);
;         const float rs = rsqrtf(rss[token] * (1.f / 1024.f) + 1e-6f);
; #pragma unroll
;         for (int bj = 0; bj < 2; bj++)
; #pragma unroll
;           for (int n = 0; n < 2; n++) {
;             const int f = EPI_COL(u, bj, n);
;             const float v0 = fmaxf(acc[ai][bj][m][n][0] * rs, 0.f), v1 = fmaxf(acc[ai][bj][m][n][1] * rs, 0.f);
;             const float v2 = fmaxf(acc[ai][bj][m][n][2] * rs, 0.f), v3 = fmaxf(acc[ai][bj][m][n][3] * rs, 0.f);
;             uint2 o; o.x = pack2(v0 * v0, v1 * v1); o.y = pack2(v2 * v2, v3 * v3);
;             *(uint2*)(H + token * 4096 + f) = o;
;           }
	v_cvt_pk_bf16_f32 v117, v120, v121
	v_cvt_pk_bf16_f32 v118, v122, v123
	v_cvt_pk_bf16_f32 v119, v124, v125
	v_cvt_pk_bf16_f32 v120, v126, v127
	v_cvt_pk_bf16_f32 v121, v128, v129
	v_permlane16_swap_b32_e32 v114, v116
	v_permlane16_swap_b32_e32 v115, v117
	v_permlane16_swap_b32_e32 v118, v120
	v_permlane16_swap_b32_e32 v119, v121
	global_store_dwordx4 v[164:165], v[114:117], off
	global_store_dwordx4 v[164:165], v[118:121], off offset:256
	s_nop 1
	v_mov_b32_e32 v118, v176
	v_lshlrev_b64 v[116:117], 13, v[162:163]
	v_or_b32_e32 v114, 32, v140
	v_lshl_add_u64 v[116:117], s[10:11], 0, v[116:117]
	v_ashrrev_i32_e32 v115, 31, v114
	v_lshl_add_u64 v[116:117], v[116:117], 0, v[138:139]
	v_fmamk_f32 v118, v118, 0x3a800000, v161
	v_mul_f32_e32 v119, 0x4b800000, v118
	v_cmp_gt_f32_e32 vcc, s53, v118
	s_nop 1
	v_cndmask_b32_e32 v118, v118, v119, vcc
	v_rsq_f32_e32 v120, v118
	v_lshl_add_u64 v[118:119], v[114:115], 2, s[12:13]
	v_mul_f32_e32 v121, 0x45800000, v120
	v_cndmask_b32_e32 v120, v120, v121, vcc
	v_mul_f32_e32 v110, v110, v120
	v_mul_f32_e32 v111, v111, v120
	v_mul_f32_e32 v112, v112, v120
	v_mul_f32_e32 v113, v113, v120
	v_mul_f32_e32 v106, v106, v120
	v_mul_f32_e32 v107, v107, v120
	v_mul_f32_e32 v108, v108, v120
	v_mul_f32_e32 v109, v109, v120
	v_mul_f32_e32 v121, v102, v120
	v_mul_f32_e32 v122, v103, v120
	v_mul_f32_e32 v123, v104, v120
	v_mul_f32_e32 v124, v105, v120
	v_mul_f32_e32 v125, v98, v120
	v_mul_f32_e32 v126, v99, v120
	v_mul_f32_e32 v127, v100, v120
	v_mul_f32_e32 v120, v101, v120
	v_max_f32_e32 v98, 0, v110
	v_max_f32_e32 v99, 0, v111
	v_max_f32_e32 v100, 0, v112
	v_max_f32_e32 v101, 0, v113
	v_max_f32_e32 v102, 0, v106
	v_max_f32_e32 v103, 0, v107
	v_max_f32_e32 v104, 0, v108
	v_max_f32_e32 v105, 0, v109
	v_max_f32_e32 v106, 0, v121
	v_max_f32_e32 v107, 0, v122
	v_max_f32_e32 v108, 0, v123
	v_max_f32_e32 v109, 0, v124
	v_max_f32_e32 v110, 0, v125
	v_max_f32_e32 v111, 0, v126
	v_max_f32_e32 v112, 0, v127
	v_max_f32_e32 v113, 0, v120
	v_pk_mul_f32 v[98:99], v[98:99], v[98:99]
	v_pk_mul_f32 v[100:101], v[100:101], v[100:101]
	v_pk_mul_f32 v[102:103], v[102:103], v[102:103]
	v_pk_mul_f32 v[104:105], v[104:105], v[104:105]
	v_pk_mul_f32 v[106:107], v[106:107], v[106:107]
	v_pk_mul_f32 v[108:109], v[108:109], v[108:109]
	v_pk_mul_f32 v[110:111], v[110:111], v[110:111]
	v_pk_mul_f32 v[112:113], v[112:113], v[112:113]
	v_cvt_pk_bf16_f32 v98, v98, v99
	v_cvt_pk_bf16_f32 v99, v100, v101
	v_cvt_pk_bf16_f32 v100, v102, v103
	v_cvt_pk_bf16_f32 v101, v104, v105
	v_cvt_pk_bf16_f32 v102, v106, v107
	v_cvt_pk_bf16_f32 v103, v108, v109
	v_cvt_pk_bf16_f32 v104, v110, v111
	v_cvt_pk_bf16_f32 v105, v112, v113
	v_permlane16_swap_b32_e32 v98, v100
	v_permlane16_swap_b32_e32 v99, v101
	v_permlane16_swap_b32_e32 v102, v104
	v_permlane16_swap_b32_e32 v103, v105
	global_store_dwordx4 v[116:117], v[98:101], off
	global_store_dwordx4 v[116:117], v[102:105], off offset:256
	s_nop 1
	v_mov_b32_e32 v102, v177
	v_lshlrev_b64 v[100:101], 13, v[114:115]
	v_or_b32_e32 v98, 48, v140
	v_lshl_add_u64 v[100:101], s[10:11], 0, v[100:101]
	v_ashrrev_i32_e32 v99, 31, v98
	v_lshl_add_u64 v[100:101], v[100:101], 0, v[138:139]
	v_fmamk_f32 v102, v102, 0x3a800000, v161
	v_mul_f32_e32 v103, 0x4b800000, v102
	v_cmp_gt_f32_e32 vcc, s53, v102
	s_nop 1
	v_cndmask_b32_e32 v102, v102, v103, vcc
	v_rsq_f32_e32 v104, v102
	v_lshl_add_u64 v[102:103], v[98:99], 2, s[12:13]
	v_mul_f32_e32 v105, 0x45800000, v104
	v_cndmask_b32_e32 v104, v104, v105, vcc
	v_mul_f32_e32 v94, v94, v104
	v_mul_f32_e32 v95, v95, v104
	v_mul_f32_e32 v96, v96, v104
	v_mul_f32_e32 v97, v97, v104
	v_mul_f32_e32 v90, v90, v104
	v_mul_f32_e32 v91, v91, v104
	v_mul_f32_e32 v92, v92, v104
	v_mul_f32_e32 v93, v93, v104
	v_mul_f32_e32 v105, v86, v104
	v_mul_f32_e32 v106, v87, v104
	v_mul_f32_e32 v107, v88, v104
	v_mul_f32_e32 v108, v89, v104
	v_mul_f32_e32 v109, v82, v104
	v_mul_f32_e32 v110, v83, v104
	v_mul_f32_e32 v111, v84, v104
	v_mul_f32_e32 v104, v85, v104
	v_max_f32_e32 v82, 0, v94
	v_max_f32_e32 v83, 0, v95
	v_max_f32_e32 v84, 0, v96
	v_max_f32_e32 v85, 0, v97
	v_max_f32_e32 v86, 0, v90
	v_max_f32_e32 v87, 0, v91
	v_max_f32_e32 v88, 0, v92
	v_max_f32_e32 v89, 0, v93
	v_max_f32_e32 v90, 0, v105
	v_max_f32_e32 v91, 0, v106
	v_max_f32_e32 v92, 0, v107
	v_max_f32_e32 v93, 0, v108
	v_max_f32_e32 v94, 0, v109
	v_max_f32_e32 v95, 0, v110
	v_max_f32_e32 v96, 0, v111
	v_max_f32_e32 v97, 0, v104
	v_pk_mul_f32 v[82:83], v[82:83], v[82:83]
	v_pk_mul_f32 v[84:85], v[84:85], v[84:85]
	v_pk_mul_f32 v[86:87], v[86:87], v[86:87]
	v_pk_mul_f32 v[88:89], v[88:89], v[88:89]
	v_pk_mul_f32 v[90:91], v[90:91], v[90:91]
	v_pk_mul_f32 v[92:93], v[92:93], v[92:93]
	v_pk_mul_f32 v[94:95], v[94:95], v[94:95]
	v_pk_mul_f32 v[96:97], v[96:97], v[96:97]
	v_cvt_pk_bf16_f32 v82, v82, v83
	v_cvt_pk_bf16_f32 v83, v84, v85
	v_cvt_pk_bf16_f32 v84, v86, v87
	v_cvt_pk_bf16_f32 v85, v88, v89
	v_cvt_pk_bf16_f32 v86, v90, v91
	v_cvt_pk_bf16_f32 v87, v92, v93
	v_cvt_pk_bf16_f32 v88, v94, v95
	v_cvt_pk_bf16_f32 v89, v96, v97
	v_permlane16_swap_b32_e32 v82, v84
	v_permlane16_swap_b32_e32 v83, v85
	v_permlane16_swap_b32_e32 v86, v88
	v_permlane16_swap_b32_e32 v87, v89
	global_store_dwordx4 v[100:101], v[82:85], off
	global_store_dwordx4 v[100:101], v[86:89], off offset:256
	s_nop 1
	v_mov_b32_e32 v86, v178
	v_lshlrev_b64 v[84:85], 13, v[98:99]
	v_add_u32_e32 v82, 0x80, v140
	v_lshl_add_u64 v[84:85], s[10:11], 0, v[84:85]
	v_ashrrev_i32_e32 v83, 31, v82
	v_lshl_add_u64 v[84:85], v[84:85], 0, v[138:139]
	v_fmamk_f32 v86, v86, 0x3a800000, v161
	v_mul_f32_e32 v87, 0x4b800000, v86
	v_cmp_gt_f32_e32 vcc, s53, v86
	s_nop 1
	v_cndmask_b32_e32 v86, v86, v87, vcc
;   __device__ __forceinline__ void operator()(const acc8_t& acc, const pg8::Unit& u, int wr, int wc, int fr, int fq) const {
;     ...
; #pragma unroll
;     for (int ai = 0; ai < 2; ai++)
; #pragma unroll
;       for (int m = 0; m < 4; m++) {
;         const size_t token = EPI_TOKEN(u, ai, m);
;         const float rs = rsqrtf(rss[token] * (1.f / 1024.f) + 1e-6f);
; #pragma unroll
;         for (int bj = 0; bj < 2; bj++)
; #pragma unroll
;           for (int n = 0; n < 2; n++) {
;             const int f = EPI_COL(u, bj, n);
;             const float v0 = fmaxf(acc[ai][bj][m][n][0] * rs, 0.f), v1 = fmaxf(acc[ai][bj][m][n][1] * rs, 0.f);
;             const float v2 = fmaxf(acc[ai][bj][m][n][2] * rs, 0.f), v3 = fmaxf(acc[ai][bj][m][n][3] * rs, 0.f);
;             uint2 o; o.x = pack2(v0 * v0, v1 * v1); o.y = pack2(v2 * v2, v3 * v3);
;             *(uint2*)(H + token * 4096 + f) = o;
;           }
	v_rsq_f32_e32 v88, v86
	v_lshl_add_u64 v[86:87], v[82:83], 2, s[12:13]
	v_mul_f32_e32 v89, 0x45800000, v88
	v_cndmask_b32_e32 v88, v88, v89, vcc
	v_mul_f32_e32 v78, v78, v88
	v_mul_f32_e32 v79, v79, v88
	v_mul_f32_e32 v80, v80, v88
	v_mul_f32_e32 v81, v81, v88
	v_mul_f32_e32 v74, v74, v88
	v_mul_f32_e32 v75, v75, v88
	v_mul_f32_e32 v76, v76, v88
	v_mul_f32_e32 v77, v77, v88
	v_mul_f32_e32 v89, v70, v88
	v_mul_f32_e32 v90, v71, v88
	v_mul_f32_e32 v91, v72, v88
	v_mul_f32_e32 v92, v73, v88
	v_mul_f32_e32 v93, v66, v88
	v_mul_f32_e32 v94, v67, v88
	v_mul_f32_e32 v95, v68, v88
	v_mul_f32_e32 v88, v69, v88
	v_max_f32_e32 v66, 0, v78
	v_max_f32_e32 v67, 0, v79
	v_max_f32_e32 v68, 0, v80
	v_max_f32_e32 v69, 0, v81
	v_max_f32_e32 v70, 0, v74
	v_max_f32_e32 v71, 0, v75
	v_max_f32_e32 v72, 0, v76
	v_max_f32_e32 v73, 0, v77
	v_max_f32_e32 v74, 0, v89
	v_max_f32_e32 v75, 0, v90
	v_max_f32_e32 v76, 0, v91
	v_max_f32_e32 v77, 0, v92
	v_max_f32_e32 v78, 0, v93
	v_max_f32_e32 v79, 0, v94
	v_max_f32_e32 v80, 0, v95
	v_max_f32_e32 v81, 0, v88
	v_pk_mul_f32 v[66:67], v[66:67], v[66:67]
	v_pk_mul_f32 v[68:69], v[68:69], v[68:69]
	v_pk_mul_f32 v[70:71], v[70:71], v[70:71]
	v_pk_mul_f32 v[72:73], v[72:73], v[72:73]
	v_pk_mul_f32 v[74:75], v[74:75], v[74:75]
	v_pk_mul_f32 v[76:77], v[76:77], v[76:77]
	v_pk_mul_f32 v[78:79], v[78:79], v[78:79]
	v_pk_mul_f32 v[80:81], v[80:81], v[80:81]
	v_cvt_pk_bf16_f32 v66, v66, v67
	v_cvt_pk_bf16_f32 v67, v68, v69
	v_cvt_pk_bf16_f32 v68, v70, v71
	v_cvt_pk_bf16_f32 v69, v72, v73
	v_cvt_pk_bf16_f32 v70, v74, v75
	v_cvt_pk_bf16_f32 v71, v76, v77
	v_cvt_pk_bf16_f32 v72, v78, v79
	v_cvt_pk_bf16_f32 v73, v80, v81
	v_permlane16_swap_b32_e32 v66, v68
	v_permlane16_swap_b32_e32 v67, v69
	v_permlane16_swap_b32_e32 v70, v72
	v_permlane16_swap_b32_e32 v71, v73
	global_store_dwordx4 v[84:85], v[66:69], off
	global_store_dwordx4 v[84:85], v[70:73], off offset:256
	s_nop 1
	v_mov_b32_e32 v70, v179
	v_lshlrev_b64 v[68:69], 13, v[82:83]
	v_add_u32_e32 v66, 0x90, v140
	v_lshl_add_u64 v[68:69], s[10:11], 0, v[68:69]
	v_ashrrev_i32_e32 v67, 31, v66
	v_lshl_add_u64 v[68:69], v[68:69], 0, v[138:139]
	v_fmamk_f32 v70, v70, 0x3a800000, v161
	v_mul_f32_e32 v71, 0x4b800000, v70
	v_cmp_gt_f32_e32 vcc, s53, v70
	s_nop 1
	v_cndmask_b32_e32 v70, v70, v71, vcc
	v_rsq_f32_e32 v72, v70
	v_lshl_add_u64 v[70:71], v[66:67], 2, s[12:13]
	v_mul_f32_e32 v73, 0x45800000, v72
	v_cndmask_b32_e32 v72, v72, v73, vcc
	v_mul_f32_e32 v62, v62, v72
	v_mul_f32_e32 v63, v63, v72
	v_mul_f32_e32 v64, v64, v72
	v_mul_f32_e32 v65, v65, v72
	v_mul_f32_e32 v58, v58, v72
	v_mul_f32_e32 v59, v59, v72
	v_mul_f32_e32 v60, v60, v72
	v_mul_f32_e32 v61, v61, v72
	v_mul_f32_e32 v73, v54, v72
	v_mul_f32_e32 v74, v55, v72
	v_mul_f32_e32 v75, v56, v72
	v_mul_f32_e32 v76, v57, v72
	v_mul_f32_e32 v77, v50, v72
	v_mul_f32_e32 v78, v51, v72
	v_mul_f32_e32 v79, v52, v72
	v_mul_f32_e32 v72, v53, v72
	v_max_f32_e32 v50, 0, v62
	v_max_f32_e32 v51, 0, v63
	v_max_f32_e32 v52, 0, v64
	v_max_f32_e32 v53, 0, v65
	v_max_f32_e32 v54, 0, v58
	v_max_f32_e32 v55, 0, v59
	v_max_f32_e32 v56, 0, v60
	v_max_f32_e32 v57, 0, v61
	v_max_f32_e32 v58, 0, v73
	v_max_f32_e32 v59, 0, v74
	v_max_f32_e32 v60, 0, v75
	v_max_f32_e32 v61, 0, v76
	v_max_f32_e32 v62, 0, v77
	v_max_f32_e32 v63, 0, v78
	v_max_f32_e32 v64, 0, v79
	v_max_f32_e32 v65, 0, v72
	v_pk_mul_f32 v[50:51], v[50:51], v[50:51]
	v_pk_mul_f32 v[52:53], v[52:53], v[52:53]
	v_pk_mul_f32 v[54:55], v[54:55], v[54:55]
	v_pk_mul_f32 v[56:57], v[56:57], v[56:57]
	v_pk_mul_f32 v[58:59], v[58:59], v[58:59]
	v_pk_mul_f32 v[60:61], v[60:61], v[60:61]
	v_pk_mul_f32 v[62:63], v[62:63], v[62:63]
	v_pk_mul_f32 v[64:65], v[64:65], v[64:65]
	v_cvt_pk_bf16_f32 v50, v50, v51
	v_cvt_pk_bf16_f32 v51, v52, v53
	v_cvt_pk_bf16_f32 v52, v54, v55
	v_cvt_pk_bf16_f32 v53, v56, v57
	v_cvt_pk_bf16_f32 v54, v58, v59
	v_cvt_pk_bf16_f32 v55, v60, v61
	v_cvt_pk_bf16_f32 v56, v62, v63
	v_cvt_pk_bf16_f32 v57, v64, v65
	v_permlane16_swap_b32_e32 v50, v52
	v_permlane16_swap_b32_e32 v51, v53
	v_permlane16_swap_b32_e32 v54, v56
	v_permlane16_swap_b32_e32 v55, v57
	global_store_dwordx4 v[68:69], v[50:53], off
	global_store_dwordx4 v[68:69], v[54:57], off offset:256
	s_nop 1
	v_mov_b32_e32 v54, v180
	v_lshlrev_b64 v[52:53], 13, v[66:67]
	v_add_u32_e32 v50, 0xa0, v140
	v_lshl_add_u64 v[52:53], s[10:11], 0, v[52:53]
	v_ashrrev_i32_e32 v51, 31, v50
	v_lshl_add_u64 v[52:53], v[52:53], 0, v[138:139]
	v_fmamk_f32 v54, v54, 0x3a800000, v161
	v_mul_f32_e32 v55, 0x4b800000, v54
	v_cmp_gt_f32_e32 vcc, s53, v54
	s_nop 1
	v_cndmask_b32_e32 v54, v54, v55, vcc
	v_rsq_f32_e32 v56, v54
	v_lshl_add_u64 v[54:55], v[50:51], 2, s[12:13]
	v_mul_f32_e32 v57, 0x45800000, v56
	v_cndmask_b32_e32 v56, v56, v57, vcc
	v_mul_f32_e32 v46, v46, v56
	v_mul_f32_e32 v47, v47, v56
	v_mul_f32_e32 v48, v48, v56
	v_mul_f32_e32 v49, v49, v56
	v_mul_f32_e32 v42, v42, v56
	v_mul_f32_e32 v43, v43, v56
	v_mul_f32_e32 v44, v44, v56
	v_mul_f32_e32 v45, v45, v56
	v_mul_f32_e32 v57, v38, v56
	v_mul_f32_e32 v58, v39, v56
	v_mul_f32_e32 v59, v40, v56
	v_mul_f32_e32 v60, v41, v56
	v_mul_f32_e32 v61, v34, v56
	v_mul_f32_e32 v62, v35, v56
	v_mul_f32_e32 v63, v36, v56
	v_mul_f32_e32 v56, v37, v56
	v_max_f32_e32 v34, 0, v46
	v_max_f32_e32 v35, 0, v47
	v_max_f32_e32 v36, 0, v48
	v_max_f32_e32 v37, 0, v49
	v_max_f32_e32 v38, 0, v42
	v_max_f32_e32 v39, 0, v43
	v_max_f32_e32 v40, 0, v44
	v_max_f32_e32 v41, 0, v45
	v_max_f32_e32 v42, 0, v57
	v_max_f32_e32 v43, 0, v58
	v_max_f32_e32 v44, 0, v59
	v_max_f32_e32 v45, 0, v60
; #define PG8_WAIT_V(n) asm volatile("s_waitcnt vmcnt(" #n ")" ::: "memory")
; #define PG8_BAR __builtin_amdgcn_s_barrier()
; template <class Epi, class Sched>
; __device__ __forceinline__ void gemm_phase(PG8_LAS unsigned char* lds, const Gemm g, const Sched& S, const Epi& E) {
;     ...
;     PG8_WAIT_V(0);
;     if (wr == 0) PG8_BAR;
;     PG8_BAR;
;   __device__ __forceinline__ void operator()(const acc8_t& acc, const pg8::Unit& u, int wr, int wc, int fr, int fq) const {
;     ...
; #pragma unroll
;     for (int ai = 0; ai < 2; ai++)
; #pragma unroll
;       for (int m = 0; m < 4; m++) {
;         const size_t token = EPI_TOKEN(u, ai, m);
;         const float rs = rsqrtf(rss[token] * (1.f / 1024.f) + 1e-6f);
; #pragma unroll
;         for (int bj = 0; bj < 2; bj++)
; #pragma unroll
;           for (int n = 0; n < 2; n++) {
;             const int f = EPI_COL(u, bj, n);
;             const float v0 = fmaxf(acc[ai][bj][m][n][0] * rs, 0.f), v1 = fmaxf(acc[ai][bj][m][n][1] * rs, 0.f);
;             const float v2 = fmaxf(acc[ai][bj][m][n][2] * rs, 0.f), v3 = fmaxf(acc[ai][bj][m][n][3] * rs, 0.f);
;             uint2 o; o.x = pack2(v0 * v0, v1 * v1); o.y = pack2(v2 * v2, v3 * v3);
;             *(uint2*)(H + token * 4096 + f) = o;
;           }
	v_max_f32_e32 v46, 0, v61
	v_max_f32_e32 v47, 0, v62
	v_max_f32_e32 v48, 0, v63
	v_max_f32_e32 v49, 0, v56
	v_pk_mul_f32 v[34:35], v[34:35], v[34:35]
	v_pk_mul_f32 v[36:37], v[36:37], v[36:37]
	v_pk_mul_f32 v[38:39], v[38:39], v[38:39]
	v_pk_mul_f32 v[40:41], v[40:41], v[40:41]
	v_pk_mul_f32 v[42:43], v[42:43], v[42:43]
	v_pk_mul_f32 v[44:45], v[44:45], v[44:45]
	v_pk_mul_f32 v[46:47], v[46:47], v[46:47]
	v_pk_mul_f32 v[48:49], v[48:49], v[48:49]
	v_cvt_pk_bf16_f32 v34, v34, v35
	v_cvt_pk_bf16_f32 v35, v36, v37
	v_cvt_pk_bf16_f32 v36, v38, v39
	v_cvt_pk_bf16_f32 v37, v40, v41
	v_cvt_pk_bf16_f32 v38, v42, v43
	v_cvt_pk_bf16_f32 v39, v44, v45
	v_cvt_pk_bf16_f32 v40, v46, v47
	v_cvt_pk_bf16_f32 v41, v48, v49
	v_permlane16_swap_b32_e32 v34, v36
	v_permlane16_swap_b32_e32 v35, v37
	v_permlane16_swap_b32_e32 v38, v40
	v_permlane16_swap_b32_e32 v39, v41
	global_store_dwordx4 v[52:53], v[34:37], off
	global_store_dwordx4 v[52:53], v[38:41], off offset:256
	s_nop 1
	v_mov_b32_e32 v38, v181
	v_lshlrev_b64 v[36:37], 13, v[50:51]
	v_add_u32_e32 v34, 0xb0, v140
	v_lshl_add_u64 v[36:37], s[10:11], 0, v[36:37]
	v_ashrrev_i32_e32 v35, 31, v34
	v_lshl_add_u64 v[36:37], v[36:37], 0, v[138:139]
	v_fmamk_f32 v38, v38, 0x3a800000, v161
	v_mul_f32_e32 v39, 0x4b800000, v38
	v_cmp_gt_f32_e32 vcc, s53, v38
	s_nop 1
	v_cndmask_b32_e32 v38, v38, v39, vcc
	v_rsq_f32_e32 v40, v38
	v_lshl_add_u64 v[38:39], v[34:35], 2, s[12:13]
	v_mul_f32_e32 v41, 0x45800000, v40
	v_cndmask_b32_e32 v40, v40, v41, vcc
	v_mul_f32_e32 v30, v30, v40
	v_mul_f32_e32 v31, v31, v40
	v_mul_f32_e32 v32, v32, v40
	v_mul_f32_e32 v33, v33, v40
	v_mul_f32_e32 v26, v26, v40
	v_mul_f32_e32 v27, v27, v40
	v_mul_f32_e32 v28, v28, v40
	v_mul_f32_e32 v29, v29, v40
	v_mul_f32_e32 v41, v22, v40
	v_mul_f32_e32 v42, v23, v40
	v_mul_f32_e32 v43, v24, v40
	v_mul_f32_e32 v44, v25, v40
	v_mul_f32_e32 v45, v18, v40
	v_mul_f32_e32 v46, v19, v40
	v_mul_f32_e32 v47, v20, v40
	v_mul_f32_e32 v40, v21, v40
	v_max_f32_e32 v18, 0, v30
	v_max_f32_e32 v19, 0, v31
	v_max_f32_e32 v20, 0, v32
	v_max_f32_e32 v21, 0, v33
	v_max_f32_e32 v22, 0, v26
	v_max_f32_e32 v23, 0, v27
	v_max_f32_e32 v24, 0, v28
	v_max_f32_e32 v25, 0, v29
	v_max_f32_e32 v26, 0, v41
	v_max_f32_e32 v27, 0, v42
	v_max_f32_e32 v28, 0, v43
	v_max_f32_e32 v29, 0, v44
	v_max_f32_e32 v30, 0, v45
	v_max_f32_e32 v31, 0, v46
	v_max_f32_e32 v32, 0, v47
	v_max_f32_e32 v33, 0, v40
	v_pk_mul_f32 v[18:19], v[18:19], v[18:19]
	v_pk_mul_f32 v[20:21], v[20:21], v[20:21]
	v_pk_mul_f32 v[22:23], v[22:23], v[22:23]
	v_pk_mul_f32 v[24:25], v[24:25], v[24:25]
	v_pk_mul_f32 v[26:27], v[26:27], v[26:27]
	v_pk_mul_f32 v[28:29], v[28:29], v[28:29]
	v_pk_mul_f32 v[30:31], v[30:31], v[30:31]
	v_pk_mul_f32 v[32:33], v[32:33], v[32:33]
	v_cvt_pk_bf16_f32 v18, v18, v19
	v_cvt_pk_bf16_f32 v19, v20, v21
	v_cvt_pk_bf16_f32 v20, v22, v23
	v_cvt_pk_bf16_f32 v21, v24, v25
	v_cvt_pk_bf16_f32 v22, v26, v27
	v_cvt_pk_bf16_f32 v23, v28, v29
	v_cvt_pk_bf16_f32 v24, v30, v31
	v_cvt_pk_bf16_f32 v25, v32, v33
	v_permlane16_swap_b32_e32 v18, v20
	v_permlane16_swap_b32_e32 v19, v21
	v_permlane16_swap_b32_e32 v22, v24
	v_permlane16_swap_b32_e32 v23, v25
	global_store_dwordx4 v[36:37], v[18:21], off
	global_store_dwordx4 v[36:37], v[22:25], off offset:256
	s_nop 1
	v_mov_b32_e32 v18, v182
	s_and_b64 vcc, exec, s[4:5]
	v_fmamk_f32 v18, v18, 0x3a800000, v161
	v_mul_f32_e32 v19, 0x4b800000, v18
	v_cmp_gt_f32_e64 s[4:5], s53, v18
	s_nop 1
	v_cndmask_b32_e64 v18, v18, v19, s[4:5]
	v_rsq_f32_e32 v20, v18
	v_lshlrev_b64 v[18:19], 13, v[34:35]
	v_lshl_add_u64 v[18:19], s[10:11], 0, v[18:19]
	v_lshl_add_u64 v[18:19], v[18:19], 0, v[138:139]
	v_mul_f32_e32 v21, 0x45800000, v20
	v_cndmask_b32_e64 v20, v20, v21, s[4:5]
	v_mul_f32_e32 v14, v14, v20
	v_mul_f32_e32 v15, v15, v20
	v_mul_f32_e32 v16, v16, v20
	v_mul_f32_e32 v17, v17, v20
	v_mul_f32_e32 v10, v10, v20
	v_mul_f32_e32 v11, v11, v20
	v_mul_f32_e32 v12, v12, v20
	v_mul_f32_e32 v13, v13, v20
	v_mul_f32_e32 v21, v6, v20
	v_mul_f32_e32 v22, v7, v20
	v_mul_f32_e32 v23, v8, v20
	v_mul_f32_e32 v24, v9, v20
	v_mul_f32_e32 v25, v2, v20
	v_mul_f32_e32 v26, v3, v20
	v_mul_f32_e32 v27, v4, v20
	v_mul_f32_e32 v20, v5, v20
	v_max_f32_e32 v2, 0, v14
	v_max_f32_e32 v3, 0, v15
	v_max_f32_e32 v4, 0, v16
	v_max_f32_e32 v5, 0, v17
	v_max_f32_e32 v6, 0, v10
	v_max_f32_e32 v7, 0, v11
	v_max_f32_e32 v8, 0, v12
	v_max_f32_e32 v9, 0, v13
	v_max_f32_e32 v10, 0, v21
	v_max_f32_e32 v11, 0, v22
	v_max_f32_e32 v12, 0, v23
	v_max_f32_e32 v13, 0, v24
	v_max_f32_e32 v14, 0, v25
	v_max_f32_e32 v15, 0, v26
	v_max_f32_e32 v16, 0, v27
	v_max_f32_e32 v17, 0, v20
	v_pk_mul_f32 v[2:3], v[2:3], v[2:3]
	v_pk_mul_f32 v[4:5], v[4:5], v[4:5]
	v_pk_mul_f32 v[6:7], v[6:7], v[6:7]
	v_pk_mul_f32 v[8:9], v[8:9], v[8:9]
	v_pk_mul_f32 v[10:11], v[10:11], v[10:11]
	v_pk_mul_f32 v[12:13], v[12:13], v[12:13]
	v_pk_mul_f32 v[14:15], v[14:15], v[14:15]
	v_pk_mul_f32 v[16:17], v[16:17], v[16:17]
	v_cvt_pk_bf16_f32 v2, v2, v3
	v_cvt_pk_bf16_f32 v3, v4, v5
	v_cvt_pk_bf16_f32 v4, v6, v7
	v_cvt_pk_bf16_f32 v5, v8, v9
	v_cvt_pk_bf16_f32 v6, v10, v11
	v_cvt_pk_bf16_f32 v7, v12, v13
	v_cvt_pk_bf16_f32 v8, v14, v15
	v_cvt_pk_bf16_f32 v9, v16, v17
	v_permlane16_swap_b32_e32 v2, v4
	v_permlane16_swap_b32_e32 v3, v5
	v_permlane16_swap_b32_e32 v6, v8
	v_permlane16_swap_b32_e32 v7, v9
	global_store_dwordx4 v[18:19], v[2:5], off
	global_store_dwordx4 v[18:19], v[6:9], off offset:256
	s_nop 1
	s_cbranch_vccz .LBB0_794
	s_waitcnt vmcnt(0)
	s_cmpk_gt_u32 s33, 0xff
	s_cbranch_scc1 .LBB0_804
	s_barrier
